# attention second half: barrier + V DMA + (guarded) next K DMA moved in front of the last PV group; first K DMA of a unit issued at the prologue end
# baseline (speedup 1.0000x reference)
.LBB0_432:
	s_ashr_i32 s69, s59, 6
	s_lshl_b32 s3, s59, 8
	s_lshl_b32 s2, s69, 11
	s_and_b32 s3, s3, 0x700
	s_bfe_u32 s6, s59, 0x10005
	s_or_b32 s26, s2, s3
	s_lshl_b32 s3, s59, 4
	s_ashr_i32 s27, s26, 31
	s_lshl_b32 s2, s6, 9
	s_and_b32 s3, s3, 0x180
	s_lshl_b32 s68, s6, 8
	s_or_b32 s63, s2, s3
	s_lshl_b64 s[2:3], s[26:27], 11
	s_add_u32 s2, s22, s2
	s_addc_u32 s3, s23, s3
	s_lshl_b32 s7, s63, 1
	s_add_u32 s8, s2, s7
	s_mul_i32 s2, s69, 0x1200
	s_addc_u32 s9, s3, 0
	s_mul_hi_i32 s3, s69, 0x1200
	s_or_b32 s2, s2, s6
	v_mov_b32_e32 v68, v208
	s_lshl_b64 s[6:7], s[2:3], 8
	s_add_u32 s2, s24, s6
	v_ashrrev_i32_e32 v16, 4, v68
	v_lshlrev_b32_e32 v22, 3, v68
	v_add_u32_e32 v18, 32, v16
	s_addc_u32 s3, s25, s7
	v_and_b32_e32 v0, 0x78, v22
	v_ashrrev_i32_e32 v17, 31, v16
	v_ashrrev_i32_e32 v19, 31, v18
	s_add_u32 s6, s1, s6
	v_lshlrev_b32_e32 v23, 1, v0
	v_lshlrev_b64 v[48:49], 9, v[16:17]
	v_lshlrev_b64 v[8:9], 9, v[18:19]
	s_addc_u32 s7, s54, s7
	v_or_b32_e32 v50, v48, v23
	v_mov_b32_e32 v51, v49
	v_or_b32_e32 v8, v8, v23
	v_ashrrev_i32_e32 v155, 6, v68
	s_add_u32 s82, s2, 0x10000
	s_addc_u32 s83, s3, 0
	s_add_u32 s84, s6, 0x10000
	s_addc_u32 s85, s7, 0
	v_lshl_add_u64 v[0:1], s[6:7], 0, v[50:51]
	v_lshl_add_u64 v[4:5], s[6:7], 0, v[8:9]
	v_lshl_add_u64 v[10:11], s[2:3], 0, v[50:51]
	v_lshl_add_u64 v[12:13], s[2:3], 0, v[8:9]
	v_and_b32_e32 v154, 31, v68
	v_lshlrev_b32_e32 v130, 5, v155
	v_lshl_add_u64 v[218:219], v[0:1], 0, s[16:17]
	v_lshl_add_u64 v[222:223], v[4:5], 0, s[16:17]
	v_lshl_add_u64 v[226:227], v[10:11], 0, s[16:17]
	v_lshl_add_u64 v[230:231], v[12:13], 0, s[16:17]
	global_load_dwordx4 v[0:3], v[0:1], off
	s_nop 0
	global_load_dwordx4 v[4:7], v[4:5], off
	s_nop 0
	global_load_dwordx4 v[8:11], v[10:11], off
	s_nop 0
	global_load_dwordx4 v[12:15], v[12:13], off
	v_or_b32_e32 v20, v130, v154
	v_ashrrev_i32_e32 v21, 31, v20
	v_bfe_u32 v153, v68, 5, 1
	v_lshlrev_b64 v[20:21], 11, v[20:21]
	v_lshl_add_u64 v[20:21], s[8:9], 0, v[20:21]
	v_lshlrev_b32_e32 v128, 4, v153
	v_lshl_add_u64 v[20:21], v[20:21], 0, v[128:129]
	global_load_dwordx4 v[124:127], v[20:21], off
	global_load_dwordx4 v[120:123], v[20:21], off offset:32
	global_load_dwordx4 v[112:115], v[20:21], off offset:64
	global_load_dwordx4 v[116:119], v[20:21], off offset:96
	global_load_dwordx4 v[108:111], v[20:21], off offset:128
	global_load_dwordx4 v[104:107], v[20:21], off offset:160
	global_load_dwordx4 v[100:103], v[20:21], off offset:192
	global_load_dwordx4 v[96:99], v[20:21], off offset:224
	global_load_dwordx4 v[218:221], v[218:219], off
	global_load_dwordx4 v[222:225], v[222:223], off
	global_load_dwordx4 v[226:229], v[226:227], off
	global_load_dwordx4 v[230:233], v[230:231], off
	v_and_b32_e32 v19, 0xfffff0, v16
	v_lshlrev_b32_e32 v24, 1, v16
	v_lshrrev_b32_e32 v25, 1, v16
	v_and_b32_e32 v26, 3, v16
	v_and_or_b32 v19, v16, 8, v19
	v_and_or_b32 v24, v16, 4, v26
	v_and_b32_e32 v25, 0xfffff0, v18
	v_and_or_b32 v25, v18, 8, v25
	v_lshlrev_b32_e32 v26, 1, v18
	v_and_b32_e32 v17, 0x70, v68
	v_bfe_u32 v22, v22, 5, 2
	v_lshlrev_b32_e32 v16, 8, v16
	v_lshlrev_b32_e32 v18, 8, v18
	v_lshrrev_b32_e32 v19, 1, v19
	v_lshlrev_b32_e32 v156, 4, v68
	v_bitop3_b32 v162, v23, v16, v17 bitop3:0xde
	v_bitop3_b32 v163, v23, v18, v17 bitop3:0xde
	v_or_b32_e32 v16, v19, v22
	v_lshrrev_b32_e32 v17, 1, v25
	v_lshlrev_b32_e32 v24, 6, v24
	v_and_b32_e32 v27, 48, v23
	v_lshlrev_b32_e32 v16, 9, v16
	v_or_b32_e32 v17, v17, v22
	v_lshlrev_b32_e32 v60, 8, v154
	v_and_b32_e32 v61, 0x70, v156
	v_or3_b32 v164, v16, v24, v27
	v_lshlrev_b32_e32 v16, 9, v17
	v_bitop3_b32 v166, v128, v60, v61 bitop3:0xde
	v_or3_b32 v165, v16, v24, v27
	s_waitcnt vmcnt(0)
	v_and_b32_e32 v62, 0x3fffffc0, v68
	v_and_b32_e32 v157, 63, v68
	v_lshlrev_b32_e32 v63, 1, v68
	v_lshl_add_u32 v131, v62, 2, v150
	v_lshlrev_b32_e32 v62, 3, v157
	v_lshl_or_b32 v158, v154, 2, v131
	s_waitcnt vmcnt(11)
	ds_write_b128 v164, v[0:3]
	s_waitcnt vmcnt(10)
	ds_write_b128 v165, v[4:7]
	s_waitcnt vmcnt(9)
	ds_write_b128 v162, v[8:11] offset:32768
	s_waitcnt vmcnt(8)
	ds_write_b128 v163, v[12:15] offset:32768
	s_waitcnt lgkmcnt(0)
	s_barrier
	ds_read_b128 v[0:3], v166 offset:32768
	ds_read_b128 v[4:7], v166 offset:40960
	s_waitcnt vmcnt(7) lgkmcnt(1)
	v_mfma_f32_32x32x16_bf16 v[32:47], v[0:3], v[124:127], 0
	v_or_b32_e32 v0, 32, v128
	v_bitop3_b32 v167, v0, v60, v61 bitop3:0xde
	v_mov_b32_e32 v159, 0
	s_waitcnt lgkmcnt(0)
	v_mfma_f32_32x32x16_bf16 v[16:31], v[4:7], v[124:127], 0
	ds_read_b128 v[0:3], v167 offset:32768
	ds_read_b128 v[4:7], v167 offset:40960
	s_waitcnt vmcnt(6) lgkmcnt(1)
	v_mfma_f32_32x32x16_bf16 v[32:47], v[0:3], v[120:123], v[32:47]
	v_or_b32_e32 v0, 64, v128
	v_bitop3_b32 v168, v0, v60, v61 bitop3:0xde
	s_waitcnt lgkmcnt(0)
	v_mfma_f32_32x32x16_bf16 v[16:31], v[4:7], v[120:123], v[16:31]
	ds_read_b128 v[0:3], v168 offset:32768
	ds_read_b128 v[4:7], v168 offset:40960
	s_waitcnt vmcnt(5) lgkmcnt(1)
	v_mfma_f32_32x32x16_bf16 v[32:47], v[0:3], v[112:115], v[32:47]
	v_or_b32_e32 v0, 0x60, v128
	v_bitop3_b32 v169, v0, v60, v61 bitop3:0xde
	s_waitcnt lgkmcnt(0)
	v_mfma_f32_32x32x16_bf16 v[16:31], v[4:7], v[112:115], v[16:31]
	ds_read_b128 v[0:3], v169 offset:32768
	ds_read_b128 v[4:7], v169 offset:40960
	s_waitcnt vmcnt(4) lgkmcnt(1)
	v_mfma_f32_32x32x16_bf16 v[32:47], v[0:3], v[116:119], v[32:47]
	v_or_b32_e32 v0, 0x80, v128
	v_bitop3_b32 v170, v0, v60, v61 bitop3:0xde
	s_waitcnt lgkmcnt(0)
	v_mfma_f32_32x32x16_bf16 v[16:31], v[4:7], v[116:119], v[16:31]
	ds_read_b128 v[0:3], v170 offset:32768
	ds_read_b128 v[4:7], v170 offset:40960
	s_waitcnt vmcnt(3) lgkmcnt(1)
	v_mfma_f32_32x32x16_bf16 v[32:47], v[0:3], v[108:111], v[32:47]
	v_or_b32_e32 v0, 0xa0, v128
	v_bitop3_b32 v171, v0, v60, v61 bitop3:0xde
	s_waitcnt lgkmcnt(0)
	v_mfma_f32_32x32x16_bf16 v[16:31], v[4:7], v[108:111], v[16:31]
	ds_read_b128 v[0:3], v171 offset:32768
	ds_read_b128 v[4:7], v171 offset:40960
	s_waitcnt vmcnt(2) lgkmcnt(1)
	v_mfma_f32_32x32x16_bf16 v[32:47], v[0:3], v[104:107], v[32:47]
	v_or_b32_e32 v0, 0xc0, v128
	v_bitop3_b32 v172, v0, v60, v61 bitop3:0xde
	ds_read_b128 v[52:55], v172 offset:32768
	ds_read_b128 v[56:59], v172 offset:40960
	s_waitcnt lgkmcnt(2)
	v_mfma_f32_32x32x16_bf16 v[16:31], v[4:7], v[104:107], v[16:31]
	v_mov_b64_e32 v[0:1], s[36:37]
	v_mov_b64_e32 v[14:15], s[50:51]
	v_mov_b64_e32 v[2:3], s[38:39]
	v_mov_b64_e32 v[4:5], s[40:41]
	v_mov_b64_e32 v[6:7], s[42:43]
	v_mov_b64_e32 v[8:9], s[44:45]
	v_mov_b64_e32 v[10:11], s[46:47]
	s_waitcnt vmcnt(1) lgkmcnt(1)
	v_mfma_f32_32x32x16_bf16 v[32:47], v[52:55], v[100:103], v[32:47]
	v_or_b32_e32 v52, 0xe0, v128
	v_bitop3_b32 v173, v52, v60, v61 bitop3:0xde
	ds_read_b128 v[52:55], v173 offset:32768
	v_lshl_add_u64 v[60:61], v[50:51], 0, s[16:17]
	v_lshl_add_u64 v[50:51], v[50:51], 0, s[18:19]
	v_lshl_add_u64 v[64:65], s[2:3], 0, v[50:51]
	v_mov_b64_e32 v[12:13], s[48:49]
	s_waitcnt lgkmcnt(1)
	v_mfma_f32_32x32x16_bf16 v[16:31], v[56:59], v[100:103], v[16:31]
	v_and_b32_e32 v56, 0xc0, v156
	v_and_b32_e32 v57, 32, v63
	v_and_or_b32 v56, v62, 24, v56
	v_and_b32_e32 v58, 0x100, v62
	v_or3_b32 v161, v56, v57, v58
	ds_read_b128 v[56:59], v173 offset:40960
	v_or_b32_e32 v160, 0x4000, v161
	s_waitcnt vmcnt(0) lgkmcnt(1)
	v_mfma_f32_32x32x16_bf16 v[32:47], v[52:55], v[96:99], v[32:47]
	v_lshl_add_u64 v[54:55], s[2:3], 0, v[60:61]
	v_lshl_add_u64 v[52:53], s[6:7], 0, v[60:61]
	v_lshl_add_u64 v[60:61], s[6:7], 0, v[50:51]
	s_nop 0
	v_cmp_gt_u32_e64 s[6:7], 32, v157
	s_waitcnt lgkmcnt(0)
	v_mfma_f32_32x32x16_bf16 v[16:31], v[56:59], v[96:99], v[16:31]
	s_nop 0
	v_max_f32_e32 v58, v33, v33
	v_max_f32_e32 v59, v32, v32
	v_max_f32_e32 v58, v59, v58
	v_max3_f32 v58, v58, v34, v35
	v_max3_f32 v58, v58, v36, v37
	v_max3_f32 v58, v58, v38, v39
	v_max3_f32 v58, v58, v40, v41
	v_max3_f32 v58, v58, v42, v43
	v_max3_f32 v58, v58, v44, v45
	v_max3_f32 v58, v58, v46, v47
	v_max3_f32 v58, v58, v16, v17
	v_max3_f32 v58, v58, v18, v19
	v_max3_f32 v58, v58, v20, v21
	v_max3_f32 v58, v58, v22, v23
	v_max3_f32 v58, v58, v24, v25
	v_max3_f32 v58, v58, v26, v27
	v_max3_f32 v58, v58, v28, v29
	v_max3_f32 v58, v58, v30, v31
	v_mov_b32_e32 v59, v58
	s_nop 1
	v_permlane32_swap_b32_e32 v58, v59
	v_max_f32_e32 v59, v59, v59
	v_max_f32_e32 v58, v58, v58
	v_max_f32_e32 v58, v58, v59
	v_add_f32_e32 v59, 0x7149f2ca, v58
	v_max_f32_e32 v58, 0xf149f2ca, v58
	v_cmp_ge_f32_e32 vcc, s15, v59
	v_sub_f32_e32 v59, 0xf149f2ca, v58
	v_mul_f32_e32 v59, 0x3e0293ee, v59
	v_exp_f32_e32 v59, v59
	s_cmp_eq_u64 vcc, exec
	s_cselect_b64 vcc, -1, 0
	v_cndmask_b32_e32 v175, v58, v151, vcc
	v_mul_f32_e32 v58, 0xbe0293ee, v175
	v_cndmask_b32_e64 v174, v59, 1.0, vcc
	v_mov_b32_e32 v59, v58
	v_fmac_f32_e32 v59, 0x3e0293ee, v47
	v_fmamk_f32 v32, v32, 0x3e0293ee, v58
	v_fmamk_f32 v33, v33, 0x3e0293ee, v58
	v_fmamk_f32 v34, v34, 0x3e0293ee, v58
	v_fmamk_f32 v35, v35, 0x3e0293ee, v58
	v_fmamk_f32 v36, v36, 0x3e0293ee, v58
	v_fmamk_f32 v37, v37, 0x3e0293ee, v58
	v_fmamk_f32 v38, v38, 0x3e0293ee, v58
	v_fmamk_f32 v39, v39, 0x3e0293ee, v58
	v_fmamk_f32 v40, v40, 0x3e0293ee, v58
	v_fmamk_f32 v41, v41, 0x3e0293ee, v58
	v_fmamk_f32 v42, v42, 0x3e0293ee, v58
	v_fmamk_f32 v43, v43, 0x3e0293ee, v58
	v_fmamk_f32 v44, v44, 0x3e0293ee, v58
	v_fmamk_f32 v45, v45, 0x3e0293ee, v58
	v_fmamk_f32 v46, v46, 0x3e0293ee, v58
	v_pk_fma_f32 v[140:141], v[18:19], s[14:15], v[58:59] op_sel_hi:[1,0,0]
	v_and_b32_e32 v18, 15, v68
	v_pk_fma_f32 v[142:143], v[16:17], s[14:15], v[58:59] op_sel_hi:[1,0,0]
	v_exp_f32_e32 v190, v32
	v_exp_f32_e32 v191, v33
	v_exp_f32_e32 v192, v34
	v_exp_f32_e32 v193, v35
	v_exp_f32_e32 v194, v36
	v_exp_f32_e32 v196, v37
	v_exp_f32_e32 v195, v38
	v_exp_f32_e32 v197, v39
	v_exp_f32_e32 v182, v40
	v_exp_f32_e32 v183, v41
	v_exp_f32_e32 v184, v42
	v_exp_f32_e32 v186, v43
	v_exp_f32_e32 v185, v44
	v_exp_f32_e32 v187, v45
	v_exp_f32_e32 v188, v46
	v_exp_f32_e32 v189, v59
	v_mad_i64_i32 v[16:17], s[2:3], s69, v152, v[48:49]
	v_lshlrev_b32_e32 v18, 4, v18
	s_waitcnt vmcnt(0)
	v_or3_b32 v16, v16, s68, v18
	v_pk_fma_f32 v[144:145], v[30:31], s[14:15], v[58:59] op_sel_hi:[1,0,0]
	v_pk_fma_f32 v[146:147], v[28:29], s[14:15], v[58:59] op_sel_hi:[1,0,0]
	v_pk_fma_f32 v[148:149], v[26:27], s[14:15], v[58:59] op_sel_hi:[1,0,0]
	v_pk_fma_f32 v[134:135], v[24:25], s[14:15], v[58:59] op_sel_hi:[1,0,0]
	v_pk_fma_f32 v[136:137], v[22:23], s[14:15], v[58:59] op_sel_hi:[1,0,0]
	v_pk_fma_f32 v[138:139], v[20:21], s[14:15], v[58:59] op_sel_hi:[1,0,0]
	s_waitcnt vmcnt(3)
	ds_write_b128 v164, v[218:221] offset:16384
	s_waitcnt vmcnt(2)
	ds_write_b128 v165, v[222:225] offset:16384
	s_waitcnt vmcnt(1)
	ds_write_b128 v162, v[226:229] offset:49152
	s_waitcnt vmcnt(0)
	ds_write_b128 v163, v[230:233] offset:49152
	v_lshl_add_u64 v[132:133], s[12:13], 0, v[16:17]
	v_mov_b64_e32 v[62:63], v[14:15]
	v_mov_b64_e32 v[46:47], v[14:15]
	v_mov_b64_e32 v[30:31], v[14:15]
	s_mov_b32 s68, -1
	v_mov_b64_e32 v[60:61], v[12:13]
	v_mov_b64_e32 v[58:59], v[10:11]
	v_mov_b64_e32 v[56:57], v[8:9]
	v_mov_b64_e32 v[54:55], v[6:7]
	v_mov_b64_e32 v[52:53], v[4:5]
	v_mov_b64_e32 v[50:51], v[2:3]
	v_mov_b64_e32 v[48:49], v[0:1]
	v_mov_b64_e32 v[44:45], v[12:13]
	v_mov_b64_e32 v[42:43], v[10:11]
	v_mov_b64_e32 v[40:41], v[8:9]
	v_mov_b64_e32 v[38:39], v[6:7]
	v_mov_b64_e32 v[36:37], v[4:5]
	v_mov_b64_e32 v[34:35], v[2:3]
	v_mov_b64_e32 v[32:33], v[0:1]
	v_mov_b64_e32 v[28:29], v[12:13]
	v_mov_b64_e32 v[26:27], v[10:11]
	v_mov_b64_e32 v[24:25], v[8:9]
	v_mov_b64_e32 v[22:23], v[6:7]
	v_mov_b64_e32 v[20:21], v[4:5]
	v_mov_b64_e32 v[18:19], v[2:3]
	v_mov_b64_e32 v[16:17], v[0:1]
	s_waitcnt lgkmcnt(0)
	s_barrier
	v_lshrrev_b32_e32 v250, 4, v157
	v_and_b32_e32 v251, 15, v157
	v_lshl_add_u32 v252, v155, 3, v250
	v_xor_b32_e32 v253, v251, v250
	v_lshlrev_b32_e32 v253, 4, v253
	v_lshl_add_u32 v247, v252, 9, v253
	v_or_b32_e32 v250, 4, v250
	v_xor_b32_e32 v253, v251, v250
	v_lshlrev_b32_e32 v253, 4, v253
	v_add_u32_e32 v252, 4, v252
	v_lshl_add_u32 v248, v252, 9, v253
	v_bfe_u32 v250, v157, 2, 3
	v_lshl_add_u32 v250, v155, 3, v250
	v_lshrrev_b32_e32 v251, 5, v157
	v_and_b32_e32 v252, 3, v157
	v_lshl_add_u32 v251, v251, 2, v252
	v_lshlrev_b32_e32 v251, 4, v251
	v_lshl_add_u32 v249, v250, 9, v251
	v_readfirstlane_b32 s86, v155
	s_nop 3
	s_lshl_b32 s86, s86, 11
	s_add_u32 m0, s86, 0x8000
	s_nop 0
	global_load_lds_dwordx4 v247, s[82:83]
	s_add_u32 m0, s86, 0x8400
	s_nop 0
	global_load_lds_dwordx4 v248, s[82:83]
	s_add_u32 s82, s82, 0x8000
	s_addc_u32 s83, s83, 0
.LBB0_433:
	ds_read_b128 v[64:67], v166 offset:49152
	ds_read_b128 v[68:71], v166 offset:57344
	ds_read_b128 v[176:179], v167 offset:49152
	ds_read_b128 v[198:201], v167 offset:57344
	ds_read_b128 v[202:205], v168 offset:49152
	ds_read_b128 v[210:213], v168 offset:57344
	v_exp_f32_e32 v142, v142
	v_exp_f32_e32 v143, v143
	v_exp_f32_e32 v180, v140
	v_exp_f32_e32 v181, v141
	v_exp_f32_e32 v206, v138
	v_exp_f32_e32 v207, v135
	v_exp_f32_e32 v148, v148
	v_exp_f32_e32 v149, v149
	v_exp_f32_e32 v209, v146
	s_waitcnt lgkmcnt(5)
	v_mfma_f32_32x32x16_bf16 v[80:95], v[64:67], v[124:127], 0
	s_waitcnt lgkmcnt(4)
	v_mfma_f32_32x32x16_bf16 v[64:79], v[68:71], v[124:127], 0
	v_cvt_pk_bf16_f32 v135, v192, v193
	v_cvt_pk_bf16_f32 v138, v182, v183
	v_cvt_pk_bf16_f32 v140, v185, v187
	v_cvt_pk_bf16_f32 v141, v188, v189
	s_nop 0
	s_waitcnt lgkmcnt(3)
	v_mfma_f32_32x32x16_bf16 v[80:95], v[176:179], v[120:123], v[80:95]
	ds_read_b128 v[176:179], v169 offset:49152
	ds_read_b128 v[214:217], v169 offset:57344
	ds_read_b128 v[218:221], v170 offset:49152
	ds_read_b128 v[222:225], v170 offset:57344
	ds_read_b128 v[226:229], v171 offset:49152
	ds_read_b128 v[230:233], v171 offset:57344
	ds_read_b128 v[234:237], v172 offset:49152
	ds_read_b128 v[238:241], v172 offset:57344
	s_waitcnt lgkmcnt(10)
	v_mfma_f32_32x32x16_bf16 v[64:79], v[198:201], v[120:123], v[64:79]
	ds_read_b128 v[198:201], v173 offset:49152
	ds_read_b128 v[242:245], v173 offset:57344
	s_waitcnt lgkmcnt(11)
	v_mfma_f32_32x32x16_bf16 v[80:95], v[202:205], v[112:115], v[80:95]
	v_exp_f32_e32 v205, v134
	v_add_f32_e32 v134, v191, v190
	v_add_f32_e32 v134, v192, v134
	v_add_f32_e32 v134, v193, v134
	v_add_f32_e32 v134, v194, v134
	v_add_f32_e32 v134, v196, v134
	s_waitcnt lgkmcnt(10)
	v_mfma_f32_32x32x16_bf16 v[64:79], v[210:213], v[112:115], v[64:79]
	v_add_f32_e32 v134, v195, v134
	v_add_f32_e32 v134, v197, v134
	v_add_f32_e32 v134, v182, v134
	v_add_f32_e32 v134, v183, v134
	v_add_f32_e32 v134, v184, v134
	v_add_f32_e32 v134, v186, v134
	v_add_f32_e32 v134, v185, v134
	s_waitcnt lgkmcnt(9)
	v_mfma_f32_32x32x16_bf16 v[80:95], v[176:179], v[116:119], v[80:95]
	v_add_f32_e32 v134, v187, v134
	v_add_f32_e32 v134, v188, v134
	v_add_f32_e32 v134, v189, v134
	v_add_f32_e32 v134, v142, v134
	v_exp_f32_e32 v202, v139
	v_add_f32_e32 v134, v143, v134
	v_exp_f32_e32 v203, v136
	s_waitcnt lgkmcnt(8)
	v_mfma_f32_32x32x16_bf16 v[64:79], v[214:217], v[116:119], v[64:79]
	v_add_f32_e32 v134, v180, v134
	v_exp_f32_e32 v204, v137
	v_add_f32_e32 v134, v181, v134
	v_add_f32_e32 v134, v206, v134
	v_add_f32_e32 v134, v202, v134
	v_add_f32_e32 v134, v203, v134
	v_add_f32_e32 v134, v204, v134
	s_waitcnt lgkmcnt(7)
	v_mfma_f32_32x32x16_bf16 v[80:95], v[218:221], v[108:111], v[80:95]
	v_add_f32_e32 v134, v205, v134
	v_exp_f32_e32 v210, v147
	v_add_f32_e32 v134, v207, v134
	v_exp_f32_e32 v211, v144
	v_add_f32_e32 v134, v148, v134
	v_exp_f32_e32 v212, v145
	v_add_f32_e32 v134, v149, v134
	s_waitcnt lgkmcnt(6)
	v_mfma_f32_32x32x16_bf16 v[64:79], v[222:225], v[108:111], v[64:79]
	v_add_f32_e32 v134, v209, v134
	v_add_f32_e32 v134, v210, v134
	v_add_f32_e32 v134, v211, v134
	v_add_f32_e32 v176, v212, v134
	v_cvt_pk_bf16_f32 v134, v190, v191
	v_cvt_pk_bf16_f32 v136, v194, v196
	s_waitcnt lgkmcnt(5)
	v_mfma_f32_32x32x16_bf16 v[80:95], v[226:229], v[104:107], v[80:95]
	v_cvt_pk_bf16_f32 v137, v195, v197
	v_cvt_pk_bf16_f32 v139, v184, v186
	v_cvt_pk_bf16_f32 v142, v142, v143
	s_waitcnt lgkmcnt(4)
	v_mfma_f32_32x32x16_bf16 v[64:79], v[230:233], v[104:107], v[64:79]
	ds_read_b64_tr_b16 v[218:219], v161 offset:0
	ds_read_b64_tr_b16 v[220:221], v161 offset:2048
	ds_read_b64_tr_b16 v[222:223], v161 offset:4096
	ds_read_b64_tr_b16 v[224:225], v161 offset:6144
	ds_read_b64_tr_b16 v[226:227], v161 offset:8192
	ds_read_b64_tr_b16 v[228:229], v161 offset:10240
	ds_read_b64_tr_b16 v[230:231], v161 offset:12288
	ds_read_b64_tr_b16 v[232:233], v161 offset:14336
	v_cvt_pk_bf16_f32 v143, v180, v181
	v_cvt_pk_bf16_f32 v144, v206, v202
	v_cvt_pk_bf16_f32 v145, v203, v204
	v_cvt_pk_bf16_f32 v146, v205, v207
	v_cvt_pk_bf16_f32 v147, v148, v149
	v_cvt_pk_bf16_f32 v148, v209, v210
	v_cvt_pk_bf16_f32 v149, v211, v212
	s_waitcnt lgkmcnt(11)
	v_mfma_f32_32x32x16_bf16 v[80:95], v[234:237], v[100:103], v[80:95]
	s_waitcnt lgkmcnt(10)
	v_mfma_f32_32x32x16_bf16 v[64:79], v[238:241], v[100:103], v[64:79]
	s_waitcnt lgkmcnt(9)
	v_mfma_f32_32x32x16_bf16 v[80:95], v[198:201], v[96:99], v[80:95]
	s_waitcnt lgkmcnt(8)
	v_mfma_f32_32x32x16_bf16 v[64:79], v[242:245], v[96:99], v[64:79]
	s_waitcnt lgkmcnt(0)
	s_nop 0
	v_mfma_f32_32x32x16_bf16 v[0:15], v[134:137], v[218:221], v[0:15]
	ds_read_b64_tr_b16 v[196:197], v161 offset:0x200
	ds_read_b64_tr_b16 v[198:199], v161 offset:0xa00
	v_max_f32_e32 v234, v80, v81
	v_max3_f32 v234, v234, v82, v83
	v_max3_f32 v234, v234, v84, v85
	v_max3_f32 v234, v234, v86, v87
	v_max3_f32 v234, v234, v88, v89
	v_mfma_f32_32x32x16_bf16 v[0:15], v[138:141], v[222:225], v[0:15]
	ds_read_b64_tr_b16 v[200:201], v161 offset:0x1200
	ds_read_b64_tr_b16 v[202:203], v161 offset:0x1a00
	v_max3_f32 v234, v234, v90, v91
	v_max3_f32 v234, v234, v92, v93
	v_max3_f32 v234, v234, v94, v95
	v_max3_f32 v234, v234, v64, v65
	v_max3_f32 v234, v234, v66, v67
	v_mfma_f32_32x32x16_bf16 v[0:15], v[142:145], v[226:229], v[0:15]
	ds_read_b64_tr_b16 v[204:205], v161 offset:0x2200
	ds_read_b64_tr_b16 v[206:207], v161 offset:0x2a00
	ds_read_b64_tr_b16 v[214:215], v161 offset:0x3200
	ds_read_b64_tr_b16 v[216:217], v161 offset:0x3a00
	v_max3_f32 v234, v234, v68, v69
	v_max3_f32 v234, v234, v70, v71
	v_max3_f32 v234, v234, v72, v73
	v_max3_f32 v234, v234, v74, v75
	v_max3_f32 v234, v234, v76, v77
	s_waitcnt lgkmcnt(0)
	v_mfma_f32_32x32x16_bf16 v[0:15], v[146:149], v[230:233], v[0:15]
	v_max3_f32 v234, v234, v78, v79
	v_mov_b32_e32 v235, v234
	v_mfma_f32_32x32x16_bf16 v[48:63], v[134:137], v[196:199], v[48:63]
	ds_read_b64_tr_b16 v[196:197], v161 offset:0x400
	ds_read_b64_tr_b16 v[198:199], v161 offset:0xc00
	v_permlane32_swap_b32_e32 v234, v235
	v_max_f32_e32 v234, v234, v235
	v_mfma_f32_32x32x16_bf16 v[48:63], v[138:141], v[200:203], v[48:63]
	ds_read_b64_tr_b16 v[200:201], v161 offset:0x1400
	ds_read_b64_tr_b16 v[202:203], v161 offset:0x1c00
	v_sub_f32_e32 v235, v234, v175
	v_max_f32_e32 v234, v175, v234
	v_sub_f32_e32 v236, v175, v234
	v_mul_f32_e32 v236, 0x3e0293ee, v236
	v_mfma_f32_32x32x16_bf16 v[48:63], v[142:145], v[204:207], v[48:63]
	ds_read_b64_tr_b16 v[204:205], v161 offset:0x2400
	ds_read_b64_tr_b16 v[206:207], v161 offset:0x2c00
	ds_read_b64_tr_b16 v[210:211], v161 offset:0x3400
	ds_read_b64_tr_b16 v[212:213], v161 offset:0x3c00
	v_exp_f32_e32 v236, v236
	v_cmp_ge_f32_e32 vcc, s15, v235
	s_cmp_eq_u64 vcc, exec
	s_cselect_b64 s[8:9], -1, 0
	s_waitcnt lgkmcnt(0)
	v_mfma_f32_32x32x16_bf16 v[48:63], v[146:149], v[214:217], v[48:63]
	v_cndmask_b32_e64 v179, v236, 1.0, s[8:9]
	v_cndmask_b32_e64 v234, v234, v175, s[8:9]
	v_mul_f32_e32 v238, 0xbe0293ee, v234
	v_fmamk_f32 v88, v88, 0x3e0293ee, v238
	v_fmamk_f32 v89, v89, 0x3e0293ee, v238
	v_fmamk_f32 v80, v80, 0x3e0293ee, v238
	v_fmamk_f32 v81, v81, 0x3e0293ee, v238
	v_mfma_f32_32x32x16_bf16 v[32:47], v[134:137], v[196:199], v[32:47]
	ds_read_b64_tr_b16 v[196:197], v161 offset:0x600
	ds_read_b64_tr_b16 v[198:199], v161 offset:0xe00
	v_fmamk_f32 v82, v82, 0x3e0293ee, v238
	v_fmamk_f32 v83, v83, 0x3e0293ee, v238
	v_fmamk_f32 v84, v84, 0x3e0293ee, v238
	v_fmamk_f32 v85, v85, 0x3e0293ee, v238
	v_fmamk_f32 v86, v86, 0x3e0293ee, v238
	v_fmamk_f32 v87, v87, 0x3e0293ee, v238
	v_fmamk_f32 v90, v90, 0x3e0293ee, v238
	v_fmamk_f32 v91, v91, 0x3e0293ee, v238
	v_mfma_f32_32x32x16_bf16 v[32:47], v[138:141], v[200:203], v[32:47]
	ds_read_b64_tr_b16 v[200:201], v161 offset:0x1600
	ds_read_b64_tr_b16 v[202:203], v161 offset:0x1e00
	v_fmamk_f32 v92, v92, 0x3e0293ee, v238
	v_fmamk_f32 v93, v93, 0x3e0293ee, v238
	v_fmamk_f32 v94, v94, 0x3e0293ee, v238
	v_fmamk_f32 v95, v95, 0x3e0293ee, v238
	v_fmamk_f32 v188, v64, 0x3e0293ee, v238
	v_fmamk_f32 v189, v65, 0x3e0293ee, v238
	v_fmamk_f32 v190, v66, 0x3e0293ee, v238
	v_fmamk_f32 v191, v67, 0x3e0293ee, v238
	v_mfma_f32_32x32x16_bf16 v[32:47], v[142:145], v[204:207], v[32:47]
	ds_read_b64_tr_b16 v[204:205], v161 offset:0x2600
	ds_read_b64_tr_b16 v[206:207], v161 offset:0x2e00
	ds_read_b64_tr_b16 v[214:215], v161 offset:0x3600
	ds_read_b64_tr_b16 v[216:217], v161 offset:0x3e00
	v_fmamk_f32 v182, v70, 0x3e0293ee, v238
	v_fmamk_f32 v183, v71, 0x3e0293ee, v238
	v_fmamk_f32 v184, v72, 0x3e0293ee, v238
	v_fmamk_f32 v185, v73, 0x3e0293ee, v238
	v_fmamk_f32 v186, v74, 0x3e0293ee, v238
	v_fmamk_f32 v187, v75, 0x3e0293ee, v238
	s_waitcnt lgkmcnt(0)
	v_mfma_f32_32x32x16_bf16 v[32:47], v[146:149], v[210:213], v[32:47]
	v_fmamk_f32 v192, v68, 0x3e0293ee, v238
	v_fmamk_f32 v181, v69, 0x3e0293ee, v238
	v_fmamk_f32 v180, v76, 0x3e0293ee, v238
	s_waitcnt vmcnt(0)
	s_barrier
	s_add_u32 m0, s86, 0x0
	s_nop 0
	global_load_lds_dwordx4 v249, s[84:85]
	s_add_u32 m0, s86, 0x380
	s_nop 0
	global_load_lds_dwordx4 v249, s[84:85] offset:128
	s_add_u32 s84, s84, 0x8000
	s_addc_u32 s85, s85, 0
	s_add_u32 m0, s86, 0xc000
	s_nop 0
	global_load_lds_dwordx4 v247, s[82:83]
	s_add_u32 m0, s86, 0xc400
	s_nop 0
	global_load_lds_dwordx4 v248, s[82:83]
	s_add_u32 s82, s82, 0x8000
	s_addc_u32 s83, s83, 0
	v_mfma_f32_32x32x16_bf16 v[16:31], v[134:137], v[196:199], v[16:31]
	v_fmamk_f32 v193, v77, 0x3e0293ee, v238
	v_fmamk_f32 v194, v78, 0x3e0293ee, v238
	v_fmamk_f32 v177, v79, 0x3e0293ee, v238
	ds_read_b128 v[64:67], v166 offset:32768
	ds_read_b128 v[68:71], v166 offset:40960
	ds_read_b128 v[196:199], v167 offset:32768
	v_mov_b32_e32 v134, v234
	v_exp_f32_e32 v135, v88
	v_exp_f32_e32 v136, v89
	v_exp_f32_e32 v137, v90
	v_mfma_f32_32x32x16_bf16 v[16:31], v[138:141], v[200:203], v[16:31]
	ds_read_b128 v[200:203], v167 offset:40960
	v_exp_f32_e32 v139, v91
	v_exp_f32_e32 v138, v92
	v_exp_f32_e32 v140, v93
	v_exp_f32_e32 v141, v94
	v_mfma_f32_32x32x16_bf16 v[16:31], v[142:145], v[204:207], v[16:31]
	ds_read_b128 v[204:207], v168 offset:32768
	ds_read_b128 v[210:213], v168 offset:40960
	v_exp_f32_e32 v142, v95
	v_exp_f32_e32 v143, v80
	v_exp_f32_e32 v144, v81
	v_exp_f32_e32 v145, v82
	v_mfma_f32_32x32x16_bf16 v[16:31], v[146:149], v[214:217], v[16:31]
	v_exp_f32_e32 v146, v83
	v_exp_f32_e32 v147, v84
	v_exp_f32_e32 v149, v85
	v_exp_f32_e32 v148, v86
	v_exp_f32_e32 v175, v87
	v_cmp_gt_f32_e32 vcc, 1.0, v179
	s_nop 3
	s_cbranch_vccz .LBB0_437
	s_and_saveexec_b64 s[2:3], s[6:7]
	ds_write_b32 v158, v179 offset:128
	s_or_b64 exec, exec, s[2:3]
	s_waitcnt lgkmcnt(0)
	v_add_u32_e32 v234, v131, v128
	ds_read_b128 v[218:221], v234 offset:224
	ds_read_b128 v[222:225], v234 offset:192
	ds_read_b128 v[226:229], v234 offset:160
	ds_read_b128 v[230:233], v234 offset:128
	s_waitcnt lgkmcnt(3)
	v_pk_mul_f32 v[12:13], v[12:13], v[218:219]
	s_waitcnt lgkmcnt(2)
	v_pk_mul_f32 v[8:9], v[8:9], v[222:223]
	s_waitcnt lgkmcnt(1)
	v_pk_mul_f32 v[4:5], v[4:5], v[226:227]
	v_pk_mul_f32 v[14:15], v[14:15], v[220:221]
	v_pk_mul_f32 v[10:11], v[10:11], v[224:225]
	v_pk_mul_f32 v[6:7], v[6:7], v[228:229]
	s_waitcnt lgkmcnt(0)
	v_pk_mul_f32 v[2:3], v[2:3], v[232:233]
	v_pk_mul_f32 v[0:1], v[0:1], v[230:231]
	v_pk_mul_f32 v[60:61], v[60:61], v[218:219]
	v_pk_mul_f32 v[56:57], v[56:57], v[222:223]
	v_pk_mul_f32 v[52:53], v[52:53], v[226:227]
	v_pk_mul_f32 v[62:63], v[62:63], v[220:221]
	v_pk_mul_f32 v[58:59], v[58:59], v[224:225]
	v_pk_mul_f32 v[54:55], v[54:55], v[228:229]
	v_pk_mul_f32 v[50:51], v[50:51], v[232:233]
	v_pk_mul_f32 v[48:49], v[48:49], v[230:231]
	v_pk_mul_f32 v[44:45], v[44:45], v[218:219]
	v_pk_mul_f32 v[40:41], v[40:41], v[222:223]
	v_pk_mul_f32 v[36:37], v[36:37], v[226:227]
	v_pk_mul_f32 v[46:47], v[46:47], v[220:221]
	v_pk_mul_f32 v[42:43], v[42:43], v[224:225]
	v_pk_mul_f32 v[38:39], v[38:39], v[228:229]
	v_pk_mul_f32 v[34:35], v[34:35], v[232:233]
	v_pk_mul_f32 v[32:33], v[32:33], v[230:231]
	v_pk_mul_f32 v[28:29], v[28:29], v[218:219]
	v_pk_mul_f32 v[24:25], v[24:25], v[222:223]
	v_pk_mul_f32 v[20:21], v[20:21], v[226:227]
	v_pk_mul_f32 v[30:31], v[30:31], v[220:221]
	v_pk_mul_f32 v[26:27], v[26:27], v[224:225]
	v_pk_mul_f32 v[22:23], v[22:23], v[228:229]
	v_pk_mul_f32 v[18:19], v[18:19], v[232:233]
	v_pk_mul_f32 v[16:17], v[16:17], v[230:231]
.LBB0_437:
	v_exp_f32_e32 v188, v188
	v_exp_f32_e32 v189, v189
	v_exp_f32_e32 v190, v190
	v_exp_f32_e32 v191, v191
	v_exp_f32_e32 v192, v192
	v_exp_f32_e32 v195, v181
	v_exp_f32_e32 v182, v182
	v_exp_f32_e32 v183, v183
	v_exp_f32_e32 v184, v184
	s_waitcnt lgkmcnt(5)
	v_mfma_f32_32x32x16_bf16 v[80:95], v[64:67], v[124:127], 0
	s_waitcnt lgkmcnt(4)
	v_mfma_f32_32x32x16_bf16 v[64:79], v[68:71], v[124:127], 0
	v_exp_f32_e32 v185, v185
	v_exp_f32_e32 v186, v186
	v_exp_f32_e32 v187, v187
	v_exp_f32_e32 v193, v193
	v_exp_f32_e32 v194, v194
	v_exp_f32_e32 v177, v177
	s_waitcnt lgkmcnt(3)
	v_mfma_f32_32x32x16_bf16 v[80:95], v[196:199], v[120:123], v[80:95]
	ds_read_b128 v[196:199], v169 offset:32768
	ds_read_b128 v[214:217], v169 offset:40960
	ds_read_b128 v[218:221], v170 offset:32768
	ds_read_b128 v[222:225], v170 offset:40960
	ds_read_b128 v[226:229], v171 offset:32768
	ds_read_b128 v[230:233], v171 offset:40960
	ds_read_b128 v[234:237], v172 offset:32768
	ds_read_b128 v[238:241], v172 offset:40960
	s_waitcnt lgkmcnt(10)
	v_mfma_f32_32x32x16_bf16 v[64:79], v[200:203], v[120:123], v[64:79]
	ds_read_b128 v[200:203], v173 offset:32768
	ds_read_b128 v[242:245], v173 offset:40960
	s_waitcnt lgkmcnt(11)
	v_mfma_f32_32x32x16_bf16 v[80:95], v[204:207], v[112:115], v[80:95]
	v_exp_f32_e32 v204, v180
	v_add_f32_e32 v180, v144, v143
	v_add_f32_e32 v180, v145, v180
	v_add_f32_e32 v180, v146, v180
	v_add_f32_e32 v180, v147, v180
	v_add_f32_e32 v180, v149, v180
	s_waitcnt lgkmcnt(10)
	v_mfma_f32_32x32x16_bf16 v[64:79], v[210:213], v[112:115], v[64:79]
	v_add_f32_e32 v180, v148, v180
	v_add_f32_e32 v180, v175, v180
	v_add_f32_e32 v180, v135, v180
	v_add_f32_e32 v180, v136, v180
	v_add_f32_e32 v180, v137, v180
	v_add_f32_e32 v180, v139, v180
	v_add_f32_e32 v180, v138, v180
	s_waitcnt lgkmcnt(9)
	v_mfma_f32_32x32x16_bf16 v[80:95], v[196:199], v[116:119], v[80:95]
	v_add_f32_e32 v180, v140, v180
	v_add_f32_e32 v180, v141, v180
	v_add_f32_e32 v180, v142, v180
	v_add_f32_e32 v180, v188, v180
	v_add_f32_e32 v180, v189, v180
	v_add_f32_e32 v180, v190, v180
	v_add_f32_e32 v180, v191, v180
	s_waitcnt lgkmcnt(8)
	v_mfma_f32_32x32x16_bf16 v[64:79], v[214:217], v[116:119], v[64:79]
	v_add_f32_e32 v180, v192, v180
	v_add_f32_e32 v180, v195, v180
	v_add_f32_e32 v180, v182, v180
	v_add_f32_e32 v180, v183, v180
	v_add_f32_e32 v180, v184, v180
	v_add_f32_e32 v180, v185, v180
	v_add_f32_e32 v180, v186, v180
	s_waitcnt lgkmcnt(7)
	v_mfma_f32_32x32x16_bf16 v[80:95], v[218:221], v[108:111], v[80:95]
	v_add_f32_e32 v180, v187, v180
	v_add_f32_e32 v180, v204, v180
	v_add_f32_e32 v180, v193, v180
	v_add_f32_e32 v180, v194, v180
	v_add_f32_e32 v180, v177, v180
	s_waitcnt lgkmcnt(6)
	v_mfma_f32_32x32x16_bf16 v[64:79], v[222:225], v[108:111], v[64:79]
	v_cvt_pk_bf16_f32 v144, v143, v144
	v_cvt_pk_bf16_f32 v145, v145, v146
	v_cvt_pk_bf16_f32 v146, v147, v149
	v_cvt_pk_bf16_f32 v147, v148, v175
	v_cvt_pk_bf16_f32 v136, v135, v136
	v_cvt_pk_bf16_f32 v137, v137, v139
	v_cvt_pk_bf16_f32 v138, v138, v140
	s_waitcnt lgkmcnt(5)
	v_mfma_f32_32x32x16_bf16 v[80:95], v[226:229], v[104:107], v[80:95]
	v_cvt_pk_bf16_f32 v139, v141, v142
	v_cvt_pk_bf16_f32 v140, v188, v189
	v_cvt_pk_bf16_f32 v141, v190, v191
	v_cvt_pk_bf16_f32 v142, v192, v195
	v_cvt_pk_bf16_f32 v143, v182, v183
	v_cvt_pk_bf16_f32 v182, v184, v185
	v_cvt_pk_bf16_f32 v183, v186, v187
	s_waitcnt lgkmcnt(4)
	v_mfma_f32_32x32x16_bf16 v[64:79], v[230:233], v[104:107], v[64:79]
	ds_read_b64_tr_b16 v[218:219], v160 offset:0
	ds_read_b64_tr_b16 v[220:221], v160 offset:2048
	ds_read_b64_tr_b16 v[222:223], v160 offset:4096
	ds_read_b64_tr_b16 v[224:225], v160 offset:6144
	ds_read_b64_tr_b16 v[226:227], v160 offset:8192
	ds_read_b64_tr_b16 v[228:229], v160 offset:10240
	ds_read_b64_tr_b16 v[230:231], v160 offset:12288
	ds_read_b64_tr_b16 v[232:233], v160 offset:14336
	v_cvt_pk_bf16_f32 v184, v204, v193
	v_cvt_pk_bf16_f32 v185, v194, v177
	s_waitcnt lgkmcnt(11)
	v_mfma_f32_32x32x16_bf16 v[80:95], v[234:237], v[100:103], v[80:95]
	s_waitcnt lgkmcnt(10)
	v_mfma_f32_32x32x16_bf16 v[64:79], v[238:241], v[100:103], v[64:79]
	s_waitcnt lgkmcnt(9)
	v_mfma_f32_32x32x16_bf16 v[80:95], v[200:203], v[96:99], v[80:95]
	s_waitcnt lgkmcnt(8)
	v_mfma_f32_32x32x16_bf16 v[64:79], v[242:245], v[96:99], v[64:79]
	s_waitcnt lgkmcnt(0)
	s_nop 0
	v_mfma_f32_32x32x16_bf16 v[0:15], v[144:147], v[218:221], v[0:15]
	ds_read_b64_tr_b16 v[202:203], v160 offset:0x200
	ds_read_b64_tr_b16 v[204:205], v160 offset:0xa00
	v_max_f32_e32 v242, v80, v81
	v_max3_f32 v242, v242, v82, v83
	v_max3_f32 v242, v242, v84, v85
	v_max3_f32 v242, v242, v86, v87
	v_max3_f32 v242, v242, v88, v89
	v_mfma_f32_32x32x16_bf16 v[0:15], v[136:139], v[222:225], v[0:15]
	ds_read_b64_tr_b16 v[210:211], v160 offset:0x1200
	ds_read_b64_tr_b16 v[212:213], v160 offset:0x1a00
	v_max3_f32 v242, v242, v90, v91
	v_max3_f32 v242, v242, v92, v93
	v_max3_f32 v242, v242, v94, v95
	v_max3_f32 v242, v242, v64, v65
	v_max3_f32 v242, v242, v66, v67
	v_mfma_f32_32x32x16_bf16 v[0:15], v[140:143], v[226:229], v[0:15]
	ds_read_b64_tr_b16 v[214:215], v160 offset:0x2200
	ds_read_b64_tr_b16 v[216:217], v160 offset:0x2a00
	ds_read_b64_tr_b16 v[222:223], v160 offset:0x3200
	ds_read_b64_tr_b16 v[224:225], v160 offset:0x3a00
	v_max3_f32 v242, v242, v68, v69
	v_max3_f32 v242, v242, v70, v71
	v_max3_f32 v242, v242, v72, v73
	v_max3_f32 v242, v242, v74, v75
	v_max3_f32 v242, v242, v76, v77
	s_waitcnt lgkmcnt(0)
	v_mfma_f32_32x32x16_bf16 v[0:15], v[182:185], v[230:233], v[0:15]
	v_max3_f32 v242, v242, v78, v79
	v_mov_b32_e32 v243, v242
	v_mfma_f32_32x32x16_bf16 v[48:63], v[144:147], v[202:205], v[48:63]
	ds_read_b64_tr_b16 v[202:203], v160 offset:0x400
	ds_read_b64_tr_b16 v[204:205], v160 offset:0xc00
	v_permlane32_swap_b32_e32 v242, v243
	v_max_f32_e32 v242, v242, v243
	v_mfma_f32_32x32x16_bf16 v[48:63], v[136:139], v[210:213], v[48:63]
	ds_read_b64_tr_b16 v[210:211], v160 offset:0x1400
	ds_read_b64_tr_b16 v[212:213], v160 offset:0x1c00
	v_sub_f32_e32 v243, v242, v134
	v_max_f32_e32 v242, v134, v242
	v_sub_f32_e32 v148, v134, v242
	v_mul_f32_e32 v148, 0x3e0293ee, v148
	v_mfma_f32_32x32x16_bf16 v[48:63], v[140:143], v[214:217], v[48:63]
	ds_read_b64_tr_b16 v[214:215], v160 offset:0x2400
	ds_read_b64_tr_b16 v[216:217], v160 offset:0x2c00
	ds_read_b64_tr_b16 v[218:219], v160 offset:0x3400
	ds_read_b64_tr_b16 v[220:221], v160 offset:0x3c00
	v_exp_f32_e32 v148, v148
	v_cmp_ge_f32_e32 vcc, s15, v243
	s_cmp_eq_u64 vcc, exec
	s_cselect_b64 s[8:9], -1, 0
	s_waitcnt lgkmcnt(0)
	v_mfma_f32_32x32x16_bf16 v[48:63], v[182:185], v[222:225], v[48:63]
	v_cndmask_b32_e64 v177, v148, 1.0, s[8:9]
	v_cndmask_b32_e64 v175, v242, v134, s[8:9]
	v_mul_f32_e32 v244, 0xbe0293ee, v175
	v_fmamk_f32 v80, v80, 0x3e0293ee, v244
	v_fmamk_f32 v81, v81, 0x3e0293ee, v244
	v_fmamk_f32 v82, v82, 0x3e0293ee, v244
	v_fmamk_f32 v83, v83, 0x3e0293ee, v244
	v_mfma_f32_32x32x16_bf16 v[32:47], v[144:147], v[202:205], v[32:47]
	ds_read_b64_tr_b16 v[202:203], v160 offset:0x600
	ds_read_b64_tr_b16 v[204:205], v160 offset:0xe00
	v_fmamk_f32 v84, v84, 0x3e0293ee, v244
	v_fmamk_f32 v85, v85, 0x3e0293ee, v244
	v_fmamk_f32 v86, v86, 0x3e0293ee, v244
	v_fmamk_f32 v87, v87, 0x3e0293ee, v244
	v_fmamk_f32 v88, v88, 0x3e0293ee, v244
	v_fmamk_f32 v89, v89, 0x3e0293ee, v244
	v_fmamk_f32 v90, v90, 0x3e0293ee, v244
	v_fmamk_f32 v91, v91, 0x3e0293ee, v244
	v_mfma_f32_32x32x16_bf16 v[32:47], v[136:139], v[210:213], v[32:47]
	ds_read_b64_tr_b16 v[210:211], v160 offset:0x1600
	ds_read_b64_tr_b16 v[212:213], v160 offset:0x1e00
	v_fmamk_f32 v92, v92, 0x3e0293ee, v244
	v_fmamk_f32 v93, v93, 0x3e0293ee, v244
	v_fmamk_f32 v94, v94, 0x3e0293ee, v244
	v_fmamk_f32 v95, v95, 0x3e0293ee, v244
	v_fmamk_f32 v134, v72, 0x3e0293ee, v244
	v_fmamk_f32 v135, v73, 0x3e0293ee, v244
	v_fmamk_f32 v148, v74, 0x3e0293ee, v244
	v_fmamk_f32 v149, v75, 0x3e0293ee, v244
	v_mfma_f32_32x32x16_bf16 v[32:47], v[140:143], v[214:217], v[32:47]
	ds_read_b64_tr_b16 v[214:215], v160 offset:0x2600
	ds_read_b64_tr_b16 v[216:217], v160 offset:0x2e00
	ds_read_b64_tr_b16 v[222:223], v160 offset:0x3600
	ds_read_b64_tr_b16 v[224:225], v160 offset:0x3e00
	v_exp_f32_e32 v190, v80
	v_exp_f32_e32 v191, v81
	v_exp_f32_e32 v192, v82
	s_waitcnt lgkmcnt(0)
	v_mfma_f32_32x32x16_bf16 v[32:47], v[182:185], v[218:221], v[32:47]
	v_exp_f32_e32 v193, v83
	v_exp_f32_e32 v194, v84
	v_exp_f32_e32 v196, v85
	s_waitcnt vmcnt(0)
	s_barrier
	s_add_u32 m0, s86, 0x4000
	s_nop 0
	global_load_lds_dwordx4 v249, s[84:85]
	s_add_u32 m0, s86, 0x4380
	s_nop 0
	global_load_lds_dwordx4 v249, s[84:85] offset:128
	s_add_u32 s84, s84, 0x8000
	s_addc_u32 s85, s85, 0
	s_cmp_lt_i32 s68, 31
	s_cbranch_scc0 .Lp3_kskip
	s_add_u32 m0, s86, 0x8000
	s_nop 0
	global_load_lds_dwordx4 v247, s[82:83]
	s_add_u32 m0, s86, 0x8400
	s_nop 0
	global_load_lds_dwordx4 v248, s[82:83]
	s_add_u32 s82, s82, 0x8000
	s_addc_u32 s83, s83, 0
.Lp3_kskip:
	v_mfma_f32_32x32x16_bf16 v[16:31], v[144:147], v[202:205], v[16:31]
	v_fmamk_f32 v144, v78, 0x3e0293ee, v244
	v_fmamk_f32 v145, v79, 0x3e0293ee, v244
	v_fmamk_f32 v146, v76, 0x3e0293ee, v244
	v_fmamk_f32 v147, v77, 0x3e0293ee, v244
	v_exp_f32_e32 v195, v86
	v_exp_f32_e32 v197, v87
	v_mfma_f32_32x32x16_bf16 v[16:31], v[136:139], v[210:213], v[16:31]
	v_fmamk_f32 v136, v70, 0x3e0293ee, v244
	v_fmamk_f32 v137, v71, 0x3e0293ee, v244
	v_fmamk_f32 v138, v68, 0x3e0293ee, v244
	v_fmamk_f32 v139, v69, 0x3e0293ee, v244
	v_exp_f32_e32 v186, v91
	v_exp_f32_e32 v187, v93
	v_mfma_f32_32x32x16_bf16 v[16:31], v[140:143], v[214:217], v[16:31]
	v_fmamk_f32 v140, v66, 0x3e0293ee, v244
	v_fmamk_f32 v141, v67, 0x3e0293ee, v244
	v_fmamk_f32 v142, v64, 0x3e0293ee, v244
	v_fmamk_f32 v143, v65, 0x3e0293ee, v244
	v_exp_f32_e32 v188, v94
	v_exp_f32_e32 v189, v95
	v_mfma_f32_32x32x16_bf16 v[16:31], v[182:185], v[222:225], v[16:31]
	v_exp_f32_e32 v182, v88
	v_exp_f32_e32 v183, v89
	v_exp_f32_e32 v184, v90
	v_exp_f32_e32 v185, v92
	v_cmp_gt_f32_e32 vcc, 1.0, v177
	s_nop 3
	s_cbranch_vccz .LBB0_441
	s_and_saveexec_b64 s[2:3], s[6:7]
	ds_write_b32 v158, v177 offset:128
	s_or_b64 exec, exec, s[2:3]
	s_waitcnt lgkmcnt(0)
	v_add_u32_e32 v242, v131, v128
	ds_read_b128 v[226:229], v242 offset:224
	ds_read_b128 v[230:233], v242 offset:192
	ds_read_b128 v[234:237], v242 offset:160
	ds_read_b128 v[238:241], v242 offset:128
	s_waitcnt lgkmcnt(3)
	v_pk_mul_f32 v[12:13], v[12:13], v[226:227]
	s_waitcnt lgkmcnt(2)
	v_pk_mul_f32 v[8:9], v[8:9], v[230:231]
	s_waitcnt lgkmcnt(1)
	v_pk_mul_f32 v[4:5], v[4:5], v[234:235]
	v_pk_mul_f32 v[14:15], v[14:15], v[228:229]
	v_pk_mul_f32 v[10:11], v[10:11], v[232:233]
	v_pk_mul_f32 v[6:7], v[6:7], v[236:237]
	s_waitcnt lgkmcnt(0)
	v_pk_mul_f32 v[2:3], v[2:3], v[240:241]
	v_pk_mul_f32 v[0:1], v[0:1], v[238:239]
	v_pk_mul_f32 v[60:61], v[60:61], v[226:227]
	v_pk_mul_f32 v[56:57], v[56:57], v[230:231]
	v_pk_mul_f32 v[52:53], v[52:53], v[234:235]
	v_pk_mul_f32 v[62:63], v[62:63], v[228:229]
	v_pk_mul_f32 v[58:59], v[58:59], v[232:233]
	v_pk_mul_f32 v[54:55], v[54:55], v[236:237]
	v_pk_mul_f32 v[50:51], v[50:51], v[240:241]
	v_pk_mul_f32 v[48:49], v[48:49], v[238:239]
	v_pk_mul_f32 v[44:45], v[44:45], v[226:227]
	v_pk_mul_f32 v[40:41], v[40:41], v[230:231]
	v_pk_mul_f32 v[36:37], v[36:37], v[234:235]
	v_pk_mul_f32 v[46:47], v[46:47], v[228:229]
	v_pk_mul_f32 v[42:43], v[42:43], v[232:233]
	v_pk_mul_f32 v[38:39], v[38:39], v[236:237]
	v_pk_mul_f32 v[34:35], v[34:35], v[240:241]
	v_pk_mul_f32 v[32:33], v[32:33], v[238:239]
	v_pk_mul_f32 v[28:29], v[28:29], v[226:227]
	v_pk_mul_f32 v[24:25], v[24:25], v[230:231]
	v_pk_mul_f32 v[20:21], v[20:21], v[234:235]
	v_pk_mul_f32 v[30:31], v[30:31], v[228:229]
	v_pk_mul_f32 v[26:27], v[26:27], v[232:233]
	v_pk_mul_f32 v[22:23], v[22:23], v[236:237]
	v_pk_mul_f32 v[18:19], v[18:19], v[240:241]
	v_pk_mul_f32 v[16:17], v[16:17], v[238:239]
